# v24 + GEMM DMA issue: fill the m0-write hazard slot with the address v_lshl_add_u64 instead of s_nop (11 sites)
# baseline (speedup 1.0000x reference)
.LBB0_191:
	s_add_u32 s36, s44, 0xfffc0080
	s_addc_u32 s37, s45, -1
	s_add_i32 s38, 0, 0x10000
	v_add_u32_e32 v152, s38, v142
	ds_read_b128 v[138:141], v152
	ds_read_b128 v[144:147], v152 offset:1024
	ds_read_b128 v[148:151], v152 offset:2048
	ds_read_b128 v[152:155], v152 offset:3072
	s_cmp_eq_u32 s61, 12
	s_cselect_b32 s49, s13, s37
	s_cselect_b32 s48, s34, s36
	s_cselect_b32 s47, s9, s60
	s_cselect_b32 s46, s35, s59
	v_lshl_add_u64 v[172:173], s[44:45], 0, v[134:135]
	s_add_i32 m0, s30, 0xc000
	ds_read_b128 v[156:159], v143
	ds_read_b128 v[160:163], v143 offset:1024
	ds_read_b128 v[164:167], v143 offset:2048
	ds_read_b128 v[180:183], v143 offset:3072
	ds_read_b128 v[184:187], v143 offset:4096
	ds_read_b128 v[188:191], v143 offset:5120
	ds_read_b128 v[192:195], v143 offset:6144
	ds_read_b128 v[196:199], v143 offset:7168
	global_load_lds_dwordx4 v[172:173], off
	s_add_i32 m0, s30, 0xe000
	v_lshl_add_u64 v[172:173], s[44:45], 0, v[136:137]
	global_load_lds_dwordx4 v[172:173], off
	s_waitcnt lgkmcnt(8)
	s_barrier
	s_waitcnt lgkmcnt(0)
	v_mfma_f32_16x16x32_bf16 v[124:127], v[138:141], v[156:159], v[124:127]
	v_mfma_f32_16x16x32_bf16 v[116:119], v[148:151], v[156:159], v[116:119]
	v_mfma_f32_16x16x32_bf16 v[108:111], v[138:141], v[164:167], v[108:111]
	v_mfma_f32_16x16x32_bf16 v[100:103], v[148:151], v[164:167], v[100:103]
	v_mfma_f32_16x16x32_bf16 v[92:95], v[138:141], v[184:187], v[92:95]
	v_mfma_f32_16x16x32_bf16 v[84:87], v[148:151], v[184:187], v[84:87]
	v_mfma_f32_16x16x32_bf16 v[76:79], v[138:141], v[192:195], v[76:79]
	v_mfma_f32_16x16x32_bf16 v[68:71], v[148:151], v[192:195], v[68:71]
	v_mfma_f32_16x16x32_bf16 v[124:127], v[144:147], v[160:163], v[124:127]
	v_mfma_f32_16x16x32_bf16 v[116:119], v[152:155], v[160:163], v[116:119]
	v_mfma_f32_16x16x32_bf16 v[108:111], v[144:147], v[180:183], v[108:111]
	v_mfma_f32_16x16x32_bf16 v[100:103], v[152:155], v[180:183], v[100:103]
	v_mfma_f32_16x16x32_bf16 v[92:95], v[144:147], v[188:191], v[92:95]
	v_mfma_f32_16x16x32_bf16 v[84:87], v[152:155], v[188:191], v[84:87]
	v_mfma_f32_16x16x32_bf16 v[76:79], v[144:147], v[196:199], v[76:79]
	v_mfma_f32_16x16x32_bf16 v[68:71], v[152:155], v[196:199], v[68:71]
	s_barrier
	s_add_i32 s39, 0, 0x14000
	v_add_u32_e32 v172, s39, v142
	s_add_i32 s36, s38, s29
	ds_read_b128 v[200:203], v172
	ds_read_b128 v[204:207], v172 offset:1024
	ds_read_b128 v[208:211], v172 offset:2048
	ds_read_b128 v[212:215], v172 offset:3072
	v_lshl_add_u64 v[172:173], s[46:47], 0, v[168:169]
	s_mov_b32 m0, s36
	v_lshl_add_u64 v[174:175], s[46:47], 0, v[128:129]
	global_load_lds_dwordx4 v[172:173], off
	s_add_i32 m0, s36, 0x2000
	s_nop 0
	global_load_lds_dwordx4 v[174:175], off
	s_barrier
	s_waitcnt lgkmcnt(0)
	v_mfma_f32_16x16x32_bf16 v[120:123], v[200:203], v[156:159], v[120:123]
	v_mfma_f32_16x16x32_bf16 v[112:115], v[208:211], v[156:159], v[112:115]
	v_mfma_f32_16x16x32_bf16 v[104:107], v[200:203], v[164:167], v[104:107]
	v_mfma_f32_16x16x32_bf16 v[96:99], v[208:211], v[164:167], v[96:99]
	v_mfma_f32_16x16x32_bf16 v[88:91], v[200:203], v[184:187], v[88:91]
	v_mfma_f32_16x16x32_bf16 v[80:83], v[208:211], v[184:187], v[80:83]
	v_mfma_f32_16x16x32_bf16 v[72:75], v[200:203], v[192:195], v[72:75]
	v_mfma_f32_16x16x32_bf16 v[64:67], v[208:211], v[192:195], v[64:67]
	v_mfma_f32_16x16x32_bf16 v[120:123], v[204:207], v[160:163], v[120:123]
	v_mfma_f32_16x16x32_bf16 v[112:115], v[212:215], v[160:163], v[112:115]
	v_mfma_f32_16x16x32_bf16 v[104:107], v[204:207], v[180:183], v[104:107]
	v_mfma_f32_16x16x32_bf16 v[96:99], v[212:215], v[180:183], v[96:99]
	v_mfma_f32_16x16x32_bf16 v[88:91], v[204:207], v[188:191], v[88:91]
	v_mfma_f32_16x16x32_bf16 v[80:83], v[212:215], v[188:191], v[80:83]
	v_mfma_f32_16x16x32_bf16 v[72:75], v[204:207], v[196:199], v[72:75]
	v_mfma_f32_16x16x32_bf16 v[64:67], v[212:215], v[196:199], v[64:67]
	s_mov_b32 m0, s30
	v_lshl_add_u64 v[176:177], s[48:49], 0, v[132:133]
	s_barrier
	ds_read_b128 v[156:159], v143 offset:16384
	ds_read_b128 v[160:163], v143 offset:17408
	ds_read_b128 v[164:167], v143 offset:18432
	ds_read_b128 v[180:183], v143 offset:19456
	ds_read_b128 v[184:187], v143 offset:20480
	ds_read_b128 v[188:191], v143 offset:21504
	ds_read_b128 v[192:195], v143 offset:22528
	ds_read_b128 v[196:199], v143 offset:23552
	global_load_lds_dwordx4 v[176:177], off
	v_lshl_add_u64 v[178:179], s[48:49], 0, v[130:131]
	s_mov_b32 m0, s31
	s_nop 0
	global_load_lds_dwordx4 v[178:179], off
	s_barrier
	s_waitcnt lgkmcnt(0)
	v_mfma_f32_16x16x32_bf16 v[60:63], v[138:141], v[156:159], v[60:63]
	v_mfma_f32_16x16x32_bf16 v[52:55], v[148:151], v[156:159], v[52:55]
	v_mfma_f32_16x16x32_bf16 v[44:47], v[138:141], v[164:167], v[44:47]
	v_mfma_f32_16x16x32_bf16 v[36:39], v[148:151], v[164:167], v[36:39]
	v_mfma_f32_16x16x32_bf16 v[28:31], v[138:141], v[184:187], v[28:31]
	v_mfma_f32_16x16x32_bf16 v[20:23], v[148:151], v[184:187], v[20:23]
	v_mfma_f32_16x16x32_bf16 v[12:15], v[138:141], v[192:195], v[12:15]
	v_mfma_f32_16x16x32_bf16 v[4:7], v[148:151], v[192:195], v[4:7]
	v_mfma_f32_16x16x32_bf16 v[60:63], v[144:147], v[160:163], v[60:63]
	v_mfma_f32_16x16x32_bf16 v[52:55], v[152:155], v[160:163], v[52:55]
	v_mfma_f32_16x16x32_bf16 v[44:47], v[144:147], v[180:183], v[44:47]
	v_mfma_f32_16x16x32_bf16 v[36:39], v[152:155], v[180:183], v[36:39]
	v_mfma_f32_16x16x32_bf16 v[28:31], v[144:147], v[188:191], v[28:31]
	v_mfma_f32_16x16x32_bf16 v[20:23], v[152:155], v[188:191], v[20:23]
	v_mfma_f32_16x16x32_bf16 v[12:15], v[144:147], v[196:199], v[12:15]
	v_mfma_f32_16x16x32_bf16 v[4:7], v[152:155], v[196:199], v[4:7]
	s_barrier
	s_add_u32 s36, s46, 0x40000
	s_addc_u32 s37, s47, 0
	s_add_i32 s38, s39, s29
	v_lshl_add_u64 v[138:139], s[36:37], 0, v[168:169]
	s_mov_b32 m0, s38
	s_nop 0
	global_load_lds_dwordx4 v[138:139], off
	s_add_i32 m0, s38, 0x2000
	v_lshl_add_u64 v[138:139], s[36:37], 0, v[128:129]
	global_load_lds_dwordx4 v[138:139], off
	s_waitcnt vmcnt(6)
	s_barrier
	v_mfma_f32_16x16x32_bf16 v[56:59], v[200:203], v[156:159], v[56:59]
	v_mfma_f32_16x16x32_bf16 v[48:51], v[208:211], v[156:159], v[48:51]
	v_mfma_f32_16x16x32_bf16 v[40:43], v[200:203], v[164:167], v[40:43]
	v_mfma_f32_16x16x32_bf16 v[32:35], v[208:211], v[164:167], v[32:35]
	v_mfma_f32_16x16x32_bf16 v[24:27], v[200:203], v[184:187], v[24:27]
	v_mfma_f32_16x16x32_bf16 v[16:19], v[208:211], v[184:187], v[16:19]
	v_mfma_f32_16x16x32_bf16 v[8:11], v[200:203], v[192:195], v[8:11]
	v_mfma_f32_16x16x32_bf16 v[0:3], v[208:211], v[192:195], v[0:3]
	v_mfma_f32_16x16x32_bf16 v[56:59], v[204:207], v[160:163], v[56:59]
	v_mfma_f32_16x16x32_bf16 v[48:51], v[212:215], v[160:163], v[48:51]
	v_mfma_f32_16x16x32_bf16 v[40:43], v[204:207], v[180:183], v[40:43]
	v_mfma_f32_16x16x32_bf16 v[32:35], v[212:215], v[180:183], v[32:35]
	v_mfma_f32_16x16x32_bf16 v[24:27], v[204:207], v[188:191], v[24:27]
	v_mfma_f32_16x16x32_bf16 v[16:19], v[212:215], v[188:191], v[16:19]
	v_mfma_f32_16x16x32_bf16 v[8:11], v[204:207], v[196:199], v[8:11]
	v_mfma_f32_16x16x32_bf16 v[0:3], v[212:215], v[196:199], v[0:3]
	s_add_i32 s38, 0, 0x18000
	v_add_u32_e32 v152, s38, v142
	s_barrier
	ds_read_b128 v[138:141], v152
	ds_read_b128 v[144:147], v152 offset:1024
	ds_read_b128 v[148:151], v152 offset:2048
	ds_read_b128 v[152:155], v152 offset:3072
	s_add_u32 s36, s48, 0x40000
	s_addc_u32 s37, s49, 0
	s_mov_b32 m0, s50
	v_lshl_add_u64 v[200:201], s[36:37], 0, v[132:133]
	ds_read_b128 v[156:159], v143 offset:32768
	ds_read_b128 v[160:163], v143 offset:33792
	ds_read_b128 v[164:167], v143 offset:34816
	ds_read_b128 v[180:183], v143 offset:35840
	ds_read_b128 v[184:187], v143 offset:36864
	ds_read_b128 v[188:191], v143 offset:37888
	ds_read_b128 v[192:195], v143 offset:38912
	ds_read_b128 v[196:199], v143 offset:39936
	global_load_lds_dwordx4 v[200:201], off
	v_lshl_add_u64 v[200:201], s[36:37], 0, v[130:131]
	s_mov_b32 m0, s51
	s_nop 0
	global_load_lds_dwordx4 v[200:201], off
	s_waitcnt lgkmcnt(8)
	s_barrier
	s_waitcnt lgkmcnt(0)
	v_mfma_f32_16x16x32_bf16 v[124:127], v[138:141], v[156:159], v[124:127]
	v_mfma_f32_16x16x32_bf16 v[116:119], v[148:151], v[156:159], v[116:119]
	v_mfma_f32_16x16x32_bf16 v[108:111], v[138:141], v[164:167], v[108:111]
	v_mfma_f32_16x16x32_bf16 v[100:103], v[148:151], v[164:167], v[100:103]
	v_mfma_f32_16x16x32_bf16 v[92:95], v[138:141], v[184:187], v[92:95]
	v_mfma_f32_16x16x32_bf16 v[84:87], v[148:151], v[184:187], v[84:87]
	v_mfma_f32_16x16x32_bf16 v[76:79], v[138:141], v[192:195], v[76:79]
	v_mfma_f32_16x16x32_bf16 v[68:71], v[148:151], v[192:195], v[68:71]
	v_mfma_f32_16x16x32_bf16 v[124:127], v[144:147], v[160:163], v[124:127]
	v_mfma_f32_16x16x32_bf16 v[116:119], v[152:155], v[160:163], v[116:119]
	v_mfma_f32_16x16x32_bf16 v[108:111], v[144:147], v[180:183], v[108:111]
	v_mfma_f32_16x16x32_bf16 v[100:103], v[152:155], v[180:183], v[100:103]
	v_mfma_f32_16x16x32_bf16 v[92:95], v[144:147], v[188:191], v[92:95]
	v_mfma_f32_16x16x32_bf16 v[84:87], v[152:155], v[188:191], v[84:87]
	v_mfma_f32_16x16x32_bf16 v[76:79], v[144:147], v[196:199], v[76:79]
	v_mfma_f32_16x16x32_bf16 v[68:71], v[152:155], v[196:199], v[68:71]
	s_barrier
	s_add_i32 s39, 0, 0x1c000
	s_add_i32 s36, s38, s29
	v_add_u32_e32 v212, s39, v142
	v_lshl_add_u64 v[172:173], v[172:173], 0, s[88:89]
	s_mov_b32 m0, s36
	ds_read_b128 v[200:203], v212
	ds_read_b128 v[204:207], v212 offset:1024
	ds_read_b128 v[208:211], v212 offset:2048
	ds_read_b128 v[212:215], v212 offset:3072
	global_load_lds_dwordx4 v[172:173], off
	s_add_i32 m0, s36, 0x2000
	v_lshl_add_u64 v[172:173], v[174:175], 0, s[88:89]
	global_load_lds_dwordx4 v[172:173], off
	s_barrier
	s_waitcnt lgkmcnt(0)
	v_mfma_f32_16x16x32_bf16 v[120:123], v[200:203], v[156:159], v[120:123]
	v_mfma_f32_16x16x32_bf16 v[112:115], v[208:211], v[156:159], v[112:115]
	v_mfma_f32_16x16x32_bf16 v[104:107], v[200:203], v[164:167], v[104:107]
	v_mfma_f32_16x16x32_bf16 v[96:99], v[208:211], v[164:167], v[96:99]
	v_mfma_f32_16x16x32_bf16 v[88:91], v[200:203], v[184:187], v[88:91]
	v_mfma_f32_16x16x32_bf16 v[80:83], v[208:211], v[184:187], v[80:83]
	v_mfma_f32_16x16x32_bf16 v[72:75], v[200:203], v[192:195], v[72:75]
	v_mfma_f32_16x16x32_bf16 v[64:67], v[208:211], v[192:195], v[64:67]
	v_mfma_f32_16x16x32_bf16 v[120:123], v[204:207], v[160:163], v[120:123]
	v_mfma_f32_16x16x32_bf16 v[112:115], v[212:215], v[160:163], v[112:115]
	v_mfma_f32_16x16x32_bf16 v[104:107], v[204:207], v[180:183], v[104:107]
	v_mfma_f32_16x16x32_bf16 v[96:99], v[212:215], v[180:183], v[96:99]
	v_mfma_f32_16x16x32_bf16 v[88:91], v[204:207], v[188:191], v[88:91]
	v_mfma_f32_16x16x32_bf16 v[80:83], v[212:215], v[188:191], v[80:83]
	v_mfma_f32_16x16x32_bf16 v[72:75], v[204:207], v[196:199], v[72:75]
	v_mfma_f32_16x16x32_bf16 v[64:67], v[212:215], v[196:199], v[64:67]
	s_mov_b32 m0, s54
	v_lshl_add_u64 v[172:173], v[176:177], 0, s[88:89]
	s_barrier
	ds_read_b128 v[156:159], v143 offset:49152
	ds_read_b128 v[160:163], v143 offset:50176
	ds_read_b128 v[164:167], v143 offset:51200
	ds_read_b128 v[180:183], v143 offset:52224
	ds_read_b128 v[184:187], v143 offset:53248
	ds_read_b128 v[188:191], v143 offset:54272
	ds_read_b128 v[192:195], v143 offset:55296
	ds_read_b128 v[196:199], v143 offset:56320
	global_load_lds_dwordx4 v[172:173], off
	v_lshl_add_u64 v[172:173], v[178:179], 0, s[88:89]
	s_mov_b32 m0, s55
	s_nop 0
	global_load_lds_dwordx4 v[172:173], off
	s_barrier
	s_waitcnt lgkmcnt(0)
	v_mfma_f32_16x16x32_bf16 v[60:63], v[138:141], v[156:159], v[60:63]
	v_mfma_f32_16x16x32_bf16 v[52:55], v[148:151], v[156:159], v[52:55]
	v_mfma_f32_16x16x32_bf16 v[44:47], v[138:141], v[164:167], v[44:47]
	v_mfma_f32_16x16x32_bf16 v[36:39], v[148:151], v[164:167], v[36:39]
	v_mfma_f32_16x16x32_bf16 v[28:31], v[138:141], v[184:187], v[28:31]
	v_mfma_f32_16x16x32_bf16 v[20:23], v[148:151], v[184:187], v[20:23]
	v_mfma_f32_16x16x32_bf16 v[12:15], v[138:141], v[192:195], v[12:15]
	v_mfma_f32_16x16x32_bf16 v[4:7], v[148:151], v[192:195], v[4:7]
	v_mfma_f32_16x16x32_bf16 v[60:63], v[144:147], v[160:163], v[60:63]
	v_mfma_f32_16x16x32_bf16 v[52:55], v[152:155], v[160:163], v[52:55]
	v_mfma_f32_16x16x32_bf16 v[44:47], v[144:147], v[180:183], v[44:47]
	v_mfma_f32_16x16x32_bf16 v[36:39], v[152:155], v[180:183], v[36:39]
	v_mfma_f32_16x16x32_bf16 v[28:31], v[144:147], v[188:191], v[28:31]
	v_mfma_f32_16x16x32_bf16 v[20:23], v[152:155], v[188:191], v[20:23]
	v_mfma_f32_16x16x32_bf16 v[12:15], v[144:147], v[196:199], v[12:15]
	v_mfma_f32_16x16x32_bf16 v[4:7], v[152:155], v[196:199], v[4:7]
	s_barrier
	s_add_u32 s36, s46, 0x40080
	s_addc_u32 s37, s47, 0
	s_add_i32 s38, s39, s29
	v_lshl_add_u64 v[138:139], s[36:37], 0, v[168:169]
	s_mov_b32 m0, s38
	s_nop 0
	global_load_lds_dwordx4 v[138:139], off
	s_add_i32 m0, s38, 0x2000
	v_lshl_add_u64 v[138:139], s[36:37], 0, v[128:129]
	global_load_lds_dwordx4 v[138:139], off
	s_waitcnt vmcnt(6)
	s_barrier
	v_mfma_f32_16x16x32_bf16 v[56:59], v[200:203], v[156:159], v[56:59]
	v_mfma_f32_16x16x32_bf16 v[48:51], v[208:211], v[156:159], v[48:51]
	v_mfma_f32_16x16x32_bf16 v[40:43], v[200:203], v[164:167], v[40:43]
	v_mfma_f32_16x16x32_bf16 v[32:35], v[208:211], v[164:167], v[32:35]
	v_mfma_f32_16x16x32_bf16 v[24:27], v[200:203], v[184:187], v[24:27]
	v_mfma_f32_16x16x32_bf16 v[16:19], v[208:211], v[184:187], v[16:19]
	v_mfma_f32_16x16x32_bf16 v[8:11], v[200:203], v[192:195], v[8:11]
	v_mfma_f32_16x16x32_bf16 v[0:3], v[208:211], v[192:195], v[0:3]
	v_mfma_f32_16x16x32_bf16 v[56:59], v[204:207], v[160:163], v[56:59]
	v_mfma_f32_16x16x32_bf16 v[48:51], v[212:215], v[160:163], v[48:51]
	v_mfma_f32_16x16x32_bf16 v[40:43], v[204:207], v[180:183], v[40:43]
	v_mfma_f32_16x16x32_bf16 v[32:35], v[212:215], v[180:183], v[32:35]
	v_mfma_f32_16x16x32_bf16 v[24:27], v[204:207], v[188:191], v[24:27]
	v_mfma_f32_16x16x32_bf16 v[16:19], v[212:215], v[188:191], v[16:19]
	v_mfma_f32_16x16x32_bf16 v[8:11], v[204:207], v[196:199], v[8:11]
	v_mfma_f32_16x16x32_bf16 v[0:3], v[212:215], v[196:199], v[0:3]
	s_add_i32 s61, s61, 2
	s_add_u32 s44, s44, 0x100
	s_addc_u32 s45, s45, 0
	s_add_u32 s59, s59, 0x100
	s_addc_u32 s60, s60, 0
	s_cmp_gt_u32 s61, 13
	s_barrier
	s_cbranch_scc0 .LBB0_191
	v_mul_f32_e32 v145, 0xbfb8aa3b, v124
	v_exp_f32_e32 v145, v145
	v_mov_b32_e32 v138, v171
	s_lshl_b32 s9, s58, 8
	v_add_f32_e32 v145, 1.0, v145
	v_rcp_f32_e32 v148, v145
	v_mul_f32_e32 v145, 0xbfb8aa3b, v125
	v_exp_f32_e32 v145, v145
	s_add_i32 s9, s9, s52
	v_and_or_b32 v144, v138, 15, s9
	s_lshl_b32 s9, s57, 7
	v_add_f32_e32 v145, 1.0, v145
	v_rcp_f32_e32 v149, v145
	v_lshrrev_b32_e32 v138, 1, v138
	v_and_or_b32 v138, v138, 24, s9
	v_or_b32_e32 v140, s53, v138
	v_pk_mul_f32 v[124:125], v[124:125], v[148:149]
	v_ashrrev_i32_e32 v141, 31, v140
	v_pk_mul_f32 v[120:121], v[124:125], v[120:121]
	v_mov_b64_e32 v[138:139], s[6:7]
	v_cvt_pk_bf16_f32 v120, v120, v121
	v_mul_f32_e32 v121, 0xbfb8aa3b, v126
	v_exp_f32_e32 v121, v121
	v_mad_i64_i32 v[146:147], s[34:35], v144, s18, v[138:139]
	v_lshlrev_b64 v[140:141], 1, v[140:141]
	v_add_f32_e32 v121, 1.0, v121
	v_rcp_f32_e32 v124, v121
	v_mul_f32_e32 v121, 0xbfb8aa3b, v127
	v_exp_f32_e32 v121, v121
	v_lshl_add_u64 v[146:147], v[146:147], 0, v[140:141]
	s_and_b64 vcc, exec, s[40:41]
	s_mov_b32 s57, s8
	v_add_f32_e32 v121, 1.0, v121
	v_rcp_f32_e32 v125, v121
	s_mov_b32 s58, s12
	s_mov_b64 s[46:47], s[42:43]
	s_mov_b64 s[44:45], s[14:15]
	v_pk_mul_f32 v[124:125], v[126:127], v[124:125]
	s_nop 0
	v_pk_mul_f32 v[122:123], v[124:125], v[122:123]
	s_nop 0
	v_cvt_pk_bf16_f32 v121, v122, v123
	v_mul_f32_e32 v122, 0xbfb8aa3b, v116
	v_mul_f32_e32 v123, 0xbfb8aa3b, v117
	v_exp_f32_e32 v122, v122
	v_exp_f32_e32 v123, v123
	v_add_f32_e32 v122, 1.0, v122
	v_add_f32_e32 v123, 1.0, v123
	v_rcp_f32_e32 v122, v122
	v_rcp_f32_e32 v123, v123
	s_nop 0
	v_pk_mul_f32 v[116:117], v[116:117], v[122:123]
	s_nop 0
	v_pk_mul_f32 v[112:113], v[116:117], v[112:113]
	s_nop 0
	v_cvt_pk_bf16_f32 v122, v112, v113
	v_mul_f32_e32 v112, 0xbfb8aa3b, v118
	v_mul_f32_e32 v113, 0xbfb8aa3b, v119
	v_exp_f32_e32 v112, v112
	v_exp_f32_e32 v113, v113
	v_add_f32_e32 v112, 1.0, v112
	v_add_f32_e32 v113, 1.0, v113
	v_rcp_f32_e32 v112, v112
	v_rcp_f32_e32 v113, v113
	s_nop 0
	v_pk_mul_f32 v[112:113], v[118:119], v[112:113]
	s_nop 0
	v_pk_mul_f32 v[112:113], v[112:113], v[114:115]
	v_mul_f32_e32 v114, 0xbfb8aa3b, v108
	v_mul_f32_e32 v115, 0xbfb8aa3b, v109
	v_exp_f32_e32 v114, v114
	v_exp_f32_e32 v115, v115
	v_cvt_pk_bf16_f32 v123, v112, v113
	v_or_b32_e32 v112, 16, v144
	v_add_f32_e32 v114, 1.0, v114
	v_add_f32_e32 v115, 1.0, v115
	v_rcp_f32_e32 v114, v114
	v_rcp_f32_e32 v115, v115
	v_mad_i64_i32 v[112:113], s[34:35], v112, s18, v[138:139]
	global_store_dwordx4 v[146:147], v[120:123], off
	v_pk_mul_f32 v[108:109], v[108:109], v[114:115]
	v_lshl_add_u64 v[112:113], v[112:113], 0, v[140:141]
	v_pk_mul_f32 v[104:105], v[108:109], v[104:105]
	s_nop 0
	v_cvt_pk_bf16_f32 v104, v104, v105
	v_mul_f32_e32 v105, 0xbfb8aa3b, v110
	v_exp_f32_e32 v105, v105
	s_nop 0
	v_add_f32_e32 v105, 1.0, v105
	v_rcp_f32_e32 v108, v105
	v_mul_f32_e32 v105, 0xbfb8aa3b, v111
	v_exp_f32_e32 v105, v105
	s_nop 0
	v_add_f32_e32 v105, 1.0, v105
	v_rcp_f32_e32 v109, v105
	s_nop 0
	v_pk_mul_f32 v[108:109], v[110:111], v[108:109]
	s_nop 0
	v_pk_mul_f32 v[106:107], v[108:109], v[106:107]
	s_nop 0
	v_cvt_pk_bf16_f32 v105, v106, v107
	v_mul_f32_e32 v106, 0xbfb8aa3b, v100
	v_mul_f32_e32 v107, 0xbfb8aa3b, v101
	v_exp_f32_e32 v106, v106
	v_exp_f32_e32 v107, v107
	v_add_f32_e32 v106, 1.0, v106
	v_add_f32_e32 v107, 1.0, v107
	v_rcp_f32_e32 v106, v106
	v_rcp_f32_e32 v107, v107
	s_nop 0
	v_pk_mul_f32 v[100:101], v[100:101], v[106:107]
	s_nop 0
	v_pk_mul_f32 v[96:97], v[100:101], v[96:97]
	s_nop 0
	v_cvt_pk_bf16_f32 v106, v96, v97
	v_mul_f32_e32 v96, 0xbfb8aa3b, v102
	v_mul_f32_e32 v97, 0xbfb8aa3b, v103
	v_exp_f32_e32 v96, v96
	v_exp_f32_e32 v97, v97
	v_add_f32_e32 v96, 1.0, v96
	v_add_f32_e32 v97, 1.0, v97
	v_rcp_f32_e32 v96, v96
	v_rcp_f32_e32 v97, v97
	s_nop 0
	v_pk_mul_f32 v[96:97], v[102:103], v[96:97]
	s_nop 0
	v_pk_mul_f32 v[96:97], v[96:97], v[98:99]
	v_mul_f32_e32 v98, 0xbfb8aa3b, v92
	v_mul_f32_e32 v99, 0xbfb8aa3b, v93
	v_exp_f32_e32 v98, v98
	v_exp_f32_e32 v99, v99
	v_cvt_pk_bf16_f32 v107, v96, v97
	v_or_b32_e32 v96, 32, v144
	v_add_f32_e32 v98, 1.0, v98
	v_add_f32_e32 v99, 1.0, v99
	v_rcp_f32_e32 v98, v98
	v_rcp_f32_e32 v99, v99
	v_mad_i64_i32 v[96:97], s[34:35], v96, s18, v[138:139]
	global_store_dwordx4 v[112:113], v[104:107], off
	v_pk_mul_f32 v[92:93], v[92:93], v[98:99]
	v_lshl_add_u64 v[96:97], v[96:97], 0, v[140:141]
	v_pk_mul_f32 v[88:89], v[92:93], v[88:89]
	s_nop 0
	v_cvt_pk_bf16_f32 v88, v88, v89
	v_mul_f32_e32 v89, 0xbfb8aa3b, v94
	v_exp_f32_e32 v89, v89
	s_nop 0
	v_add_f32_e32 v89, 1.0, v89
	v_rcp_f32_e32 v92, v89
	v_mul_f32_e32 v89, 0xbfb8aa3b, v95
	v_exp_f32_e32 v89, v89
	s_nop 0
	v_add_f32_e32 v89, 1.0, v89
	v_rcp_f32_e32 v93, v89
	s_nop 0
	v_pk_mul_f32 v[92:93], v[94:95], v[92:93]
	s_nop 0
	v_pk_mul_f32 v[90:91], v[92:93], v[90:91]
	s_nop 0
	v_cvt_pk_bf16_f32 v89, v90, v91
	v_mul_f32_e32 v90, 0xbfb8aa3b, v84
	v_mul_f32_e32 v91, 0xbfb8aa3b, v85
	v_exp_f32_e32 v90, v90
	v_exp_f32_e32 v91, v91
	v_add_f32_e32 v90, 1.0, v90
	v_add_f32_e32 v91, 1.0, v91
	v_rcp_f32_e32 v90, v90
	v_rcp_f32_e32 v91, v91
	s_nop 0
	v_pk_mul_f32 v[84:85], v[84:85], v[90:91]
	s_nop 0
	v_pk_mul_f32 v[80:81], v[84:85], v[80:81]
	s_nop 0
	v_cvt_pk_bf16_f32 v90, v80, v81
	v_mul_f32_e32 v80, 0xbfb8aa3b, v86
	v_mul_f32_e32 v81, 0xbfb8aa3b, v87
	v_exp_f32_e32 v80, v80
	v_exp_f32_e32 v81, v81
	v_add_f32_e32 v80, 1.0, v80
	v_add_f32_e32 v81, 1.0, v81
	v_rcp_f32_e32 v80, v80
	v_rcp_f32_e32 v81, v81
	s_nop 0
	v_pk_mul_f32 v[80:81], v[86:87], v[80:81]
	s_nop 0
	v_pk_mul_f32 v[80:81], v[80:81], v[82:83]
	v_mul_f32_e32 v82, 0xbfb8aa3b, v76
	v_mul_f32_e32 v83, 0xbfb8aa3b, v77
	v_exp_f32_e32 v82, v82
	v_exp_f32_e32 v83, v83
	v_cvt_pk_bf16_f32 v91, v80, v81
	v_or_b32_e32 v80, 48, v144
	v_add_f32_e32 v82, 1.0, v82
	v_add_f32_e32 v83, 1.0, v83
	v_rcp_f32_e32 v82, v82
	v_rcp_f32_e32 v83, v83
	v_mad_i64_i32 v[80:81], s[34:35], v80, s18, v[138:139]
	global_store_dwordx4 v[96:97], v[88:91], off
	v_pk_mul_f32 v[76:77], v[76:77], v[82:83]
	v_lshl_add_u64 v[80:81], v[80:81], 0, v[140:141]
	v_pk_mul_f32 v[72:73], v[76:77], v[72:73]
	s_nop 0
	v_cvt_pk_bf16_f32 v72, v72, v73
	v_mul_f32_e32 v73, 0xbfb8aa3b, v78
	v_exp_f32_e32 v73, v73
	s_nop 0
	v_add_f32_e32 v73, 1.0, v73
	v_rcp_f32_e32 v76, v73
	v_mul_f32_e32 v73, 0xbfb8aa3b, v79
	v_exp_f32_e32 v73, v73
	s_nop 0
	v_add_f32_e32 v73, 1.0, v73
	v_rcp_f32_e32 v77, v73
	s_nop 0
	v_pk_mul_f32 v[76:77], v[78:79], v[76:77]
	s_nop 0
	v_pk_mul_f32 v[74:75], v[76:77], v[74:75]
	s_nop 0
	v_cvt_pk_bf16_f32 v73, v74, v75
	v_mul_f32_e32 v74, 0xbfb8aa3b, v68
	v_mul_f32_e32 v75, 0xbfb8aa3b, v69
	v_exp_f32_e32 v74, v74
	v_exp_f32_e32 v75, v75
	v_add_f32_e32 v74, 1.0, v74
	v_add_f32_e32 v75, 1.0, v75
	v_rcp_f32_e32 v74, v74
	v_rcp_f32_e32 v75, v75
	s_nop 0
	v_pk_mul_f32 v[68:69], v[68:69], v[74:75]
	s_nop 0
	v_pk_mul_f32 v[64:65], v[68:69], v[64:65]
	s_nop 0
	v_cvt_pk_bf16_f32 v74, v64, v65
	v_mul_f32_e32 v64, 0xbfb8aa3b, v70
	v_mul_f32_e32 v65, 0xbfb8aa3b, v71
	v_exp_f32_e32 v64, v64
	v_exp_f32_e32 v65, v65
	v_add_f32_e32 v64, 1.0, v64
	v_add_f32_e32 v65, 1.0, v65
	v_rcp_f32_e32 v64, v64
	v_rcp_f32_e32 v65, v65
	s_nop 0
	v_pk_mul_f32 v[64:65], v[70:71], v[64:65]
	s_nop 0
	v_pk_mul_f32 v[64:65], v[64:65], v[66:67]
	v_mul_f32_e32 v66, 0xbfb8aa3b, v60
	v_mul_f32_e32 v67, 0xbfb8aa3b, v61
	v_exp_f32_e32 v66, v66
	v_exp_f32_e32 v67, v67
	v_cvt_pk_bf16_f32 v75, v64, v65
	v_add_u32_e32 v64, 0x80, v144
	v_add_f32_e32 v66, 1.0, v66
	v_add_f32_e32 v67, 1.0, v67
	v_rcp_f32_e32 v66, v66
	v_rcp_f32_e32 v67, v67
	v_mad_i64_i32 v[64:65], s[34:35], v64, s18, v[138:139]
	global_store_dwordx4 v[80:81], v[72:75], off
	v_pk_mul_f32 v[60:61], v[60:61], v[66:67]
	v_lshl_add_u64 v[64:65], v[64:65], 0, v[140:141]
	v_pk_mul_f32 v[56:57], v[60:61], v[56:57]
	s_nop 0
	v_cvt_pk_bf16_f32 v56, v56, v57
	v_mul_f32_e32 v57, 0xbfb8aa3b, v62
	v_exp_f32_e32 v57, v57
	s_nop 0
	v_add_f32_e32 v57, 1.0, v57
	v_rcp_f32_e32 v60, v57
	v_mul_f32_e32 v57, 0xbfb8aa3b, v63
	v_exp_f32_e32 v57, v57
	s_nop 0
	v_add_f32_e32 v57, 1.0, v57
	v_rcp_f32_e32 v61, v57
	s_nop 0
	v_pk_mul_f32 v[60:61], v[62:63], v[60:61]
	s_nop 0
	v_pk_mul_f32 v[58:59], v[60:61], v[58:59]
	s_nop 0
	v_cvt_pk_bf16_f32 v57, v58, v59
	v_mul_f32_e32 v58, 0xbfb8aa3b, v52
	v_mul_f32_e32 v59, 0xbfb8aa3b, v53
	v_exp_f32_e32 v58, v58
	v_exp_f32_e32 v59, v59
	v_add_f32_e32 v58, 1.0, v58
	v_add_f32_e32 v59, 1.0, v59
	v_rcp_f32_e32 v58, v58
	v_rcp_f32_e32 v59, v59
	s_nop 0
	v_pk_mul_f32 v[52:53], v[52:53], v[58:59]
	s_nop 0
	v_pk_mul_f32 v[48:49], v[52:53], v[48:49]
	s_nop 0
	v_cvt_pk_bf16_f32 v58, v48, v49
	v_mul_f32_e32 v48, 0xbfb8aa3b, v54
	v_mul_f32_e32 v49, 0xbfb8aa3b, v55
	v_exp_f32_e32 v48, v48
	v_exp_f32_e32 v49, v49
	v_add_f32_e32 v48, 1.0, v48
	v_add_f32_e32 v49, 1.0, v49
	v_rcp_f32_e32 v48, v48
	v_rcp_f32_e32 v49, v49
	s_nop 0
	v_pk_mul_f32 v[48:49], v[54:55], v[48:49]
	s_nop 0
	v_pk_mul_f32 v[48:49], v[48:49], v[50:51]
	v_mul_f32_e32 v50, 0xbfb8aa3b, v44
	v_mul_f32_e32 v51, 0xbfb8aa3b, v45
	v_exp_f32_e32 v50, v50
	v_exp_f32_e32 v51, v51
	v_cvt_pk_bf16_f32 v59, v48, v49
	v_add_u32_e32 v48, 0x90, v144
	v_add_f32_e32 v50, 1.0, v50
	v_add_f32_e32 v51, 1.0, v51
	v_rcp_f32_e32 v50, v50
	v_rcp_f32_e32 v51, v51
	v_mad_i64_i32 v[48:49], s[34:35], v48, s18, v[138:139]
	global_store_dwordx4 v[64:65], v[56:59], off
	v_pk_mul_f32 v[44:45], v[44:45], v[50:51]
	v_lshl_add_u64 v[48:49], v[48:49], 0, v[140:141]
	v_pk_mul_f32 v[40:41], v[44:45], v[40:41]
	s_nop 0
	v_cvt_pk_bf16_f32 v40, v40, v41
	v_mul_f32_e32 v41, 0xbfb8aa3b, v46
	v_exp_f32_e32 v41, v41
	s_nop 0
	v_add_f32_e32 v41, 1.0, v41
	v_rcp_f32_e32 v44, v41
	v_mul_f32_e32 v41, 0xbfb8aa3b, v47
	v_exp_f32_e32 v41, v41
	s_nop 0
	v_add_f32_e32 v41, 1.0, v41
	v_rcp_f32_e32 v45, v41
	s_nop 0
	v_pk_mul_f32 v[44:45], v[46:47], v[44:45]
	s_nop 0
	v_pk_mul_f32 v[42:43], v[44:45], v[42:43]
	s_nop 0
	v_cvt_pk_bf16_f32 v41, v42, v43
	v_mul_f32_e32 v42, 0xbfb8aa3b, v36
	v_mul_f32_e32 v43, 0xbfb8aa3b, v37
	v_exp_f32_e32 v42, v42
	v_exp_f32_e32 v43, v43
	v_add_f32_e32 v42, 1.0, v42
	v_add_f32_e32 v43, 1.0, v43
	v_rcp_f32_e32 v42, v42
	v_rcp_f32_e32 v43, v43
	s_nop 0
	v_pk_mul_f32 v[36:37], v[36:37], v[42:43]
	s_nop 0
	v_pk_mul_f32 v[32:33], v[36:37], v[32:33]
	s_nop 0
	v_cvt_pk_bf16_f32 v42, v32, v33
	v_mul_f32_e32 v32, 0xbfb8aa3b, v38
	v_mul_f32_e32 v33, 0xbfb8aa3b, v39
	v_exp_f32_e32 v32, v32
	v_exp_f32_e32 v33, v33
	v_add_f32_e32 v32, 1.0, v32
	v_add_f32_e32 v33, 1.0, v33
	v_rcp_f32_e32 v32, v32
	v_rcp_f32_e32 v33, v33
	s_nop 0
	v_pk_mul_f32 v[32:33], v[38:39], v[32:33]
	s_nop 0
	v_pk_mul_f32 v[32:33], v[32:33], v[34:35]
	v_mul_f32_e32 v34, 0xbfb8aa3b, v28
	v_mul_f32_e32 v35, 0xbfb8aa3b, v29
	v_exp_f32_e32 v34, v34
	v_exp_f32_e32 v35, v35
	v_cvt_pk_bf16_f32 v43, v32, v33
	v_add_u32_e32 v32, 0xa0, v144
	v_add_f32_e32 v34, 1.0, v34
	v_add_f32_e32 v35, 1.0, v35
	v_rcp_f32_e32 v34, v34
	v_rcp_f32_e32 v35, v35
	v_mad_i64_i32 v[32:33], s[34:35], v32, s18, v[138:139]
	global_store_dwordx4 v[48:49], v[40:43], off
	v_pk_mul_f32 v[28:29], v[28:29], v[34:35]
	v_lshl_add_u64 v[32:33], v[32:33], 0, v[140:141]
	v_pk_mul_f32 v[24:25], v[28:29], v[24:25]
	s_nop 0
	v_cvt_pk_bf16_f32 v24, v24, v25
	v_mul_f32_e32 v25, 0xbfb8aa3b, v30
	v_exp_f32_e32 v25, v25
	s_nop 0
	v_add_f32_e32 v25, 1.0, v25
	v_rcp_f32_e32 v28, v25
	v_mul_f32_e32 v25, 0xbfb8aa3b, v31
	v_exp_f32_e32 v25, v25
	s_nop 0
	v_add_f32_e32 v25, 1.0, v25
	v_rcp_f32_e32 v29, v25
	s_nop 0
	v_pk_mul_f32 v[28:29], v[30:31], v[28:29]
	s_nop 0
	v_pk_mul_f32 v[26:27], v[28:29], v[26:27]
	s_nop 0
	v_cvt_pk_bf16_f32 v25, v26, v27
	v_mul_f32_e32 v26, 0xbfb8aa3b, v20
	v_mul_f32_e32 v27, 0xbfb8aa3b, v21
	v_exp_f32_e32 v26, v26
	v_exp_f32_e32 v27, v27
	v_add_f32_e32 v26, 1.0, v26
	v_add_f32_e32 v27, 1.0, v27
	v_rcp_f32_e32 v26, v26
	v_rcp_f32_e32 v27, v27
	s_nop 0
	v_pk_mul_f32 v[20:21], v[20:21], v[26:27]
	s_nop 0
	v_pk_mul_f32 v[16:17], v[20:21], v[16:17]
	s_nop 0
	v_cvt_pk_bf16_f32 v26, v16, v17
	v_mul_f32_e32 v16, 0xbfb8aa3b, v22
	v_mul_f32_e32 v17, 0xbfb8aa3b, v23
	v_exp_f32_e32 v16, v16
	v_exp_f32_e32 v17, v17
	v_add_f32_e32 v16, 1.0, v16
	v_add_f32_e32 v17, 1.0, v17
	v_rcp_f32_e32 v16, v16
	v_rcp_f32_e32 v17, v17
	s_nop 0
	v_pk_mul_f32 v[16:17], v[22:23], v[16:17]
	s_nop 0
	v_pk_mul_f32 v[16:17], v[16:17], v[18:19]
	v_mul_f32_e32 v18, 0xbfb8aa3b, v12
	v_mul_f32_e32 v19, 0xbfb8aa3b, v13
	v_exp_f32_e32 v18, v18
	v_exp_f32_e32 v19, v19
	v_cvt_pk_bf16_f32 v27, v16, v17
	v_add_u32_e32 v16, 0xb0, v144
	v_add_f32_e32 v18, 1.0, v18
	v_add_f32_e32 v19, 1.0, v19
	v_rcp_f32_e32 v18, v18
	v_rcp_f32_e32 v19, v19
	v_mad_i64_i32 v[16:17], s[34:35], v16, s18, v[138:139]
	global_store_dwordx4 v[32:33], v[24:27], off
	v_pk_mul_f32 v[12:13], v[12:13], v[18:19]
	v_lshl_add_u64 v[16:17], v[16:17], 0, v[140:141]
	v_pk_mul_f32 v[8:9], v[12:13], v[8:9]
	s_nop 0
	v_cvt_pk_bf16_f32 v8, v8, v9
	v_mul_f32_e32 v9, 0xbfb8aa3b, v14
	v_exp_f32_e32 v9, v9
	s_nop 0
	v_add_f32_e32 v9, 1.0, v9
	v_rcp_f32_e32 v12, v9
	v_mul_f32_e32 v9, 0xbfb8aa3b, v15
	v_exp_f32_e32 v9, v9
	s_nop 0
	v_add_f32_e32 v9, 1.0, v9
	v_rcp_f32_e32 v13, v9
	s_nop 0
	v_pk_mul_f32 v[12:13], v[14:15], v[12:13]
	s_nop 0
	v_pk_mul_f32 v[10:11], v[12:13], v[10:11]
	s_nop 0
	v_cvt_pk_bf16_f32 v9, v10, v11
	v_mul_f32_e32 v10, 0xbfb8aa3b, v4
	v_mul_f32_e32 v11, 0xbfb8aa3b, v5
	v_exp_f32_e32 v10, v10
	v_exp_f32_e32 v11, v11
	v_add_f32_e32 v10, 1.0, v10
	v_add_f32_e32 v11, 1.0, v11
	v_rcp_f32_e32 v10, v10
	v_rcp_f32_e32 v11, v11
	s_nop 0
	v_pk_mul_f32 v[4:5], v[4:5], v[10:11]
	s_nop 0
	v_pk_mul_f32 v[0:1], v[4:5], v[0:1]
	s_nop 0
	v_cvt_pk_bf16_f32 v10, v0, v1
	v_mul_f32_e32 v0, 0xbfb8aa3b, v6
	v_mul_f32_e32 v1, 0xbfb8aa3b, v7
	v_exp_f32_e32 v0, v0
	v_exp_f32_e32 v1, v1
	v_add_f32_e32 v0, 1.0, v0
	v_add_f32_e32 v1, 1.0, v1
	v_rcp_f32_e32 v0, v0
	v_rcp_f32_e32 v1, v1
	s_nop 0
	v_pk_mul_f32 v[0:1], v[6:7], v[0:1]
	s_nop 0
	v_pk_mul_f32 v[0:1], v[0:1], v[2:3]
	s_nop 0
	v_cvt_pk_bf16_f32 v11, v0, v1
	global_store_dwordx4 v[16:17], v[8:11], off
	s_cbranch_vccz .LBB0_188
	s_waitcnt vmcnt(0)
	s_cmpk_gt_u32 s16, 0xff
	s_cbranch_scc1 .LBB0_195
	s_barrier

.LBB0_264:
	s_add_u32 s36, s50, 0xfffc0080
	s_addc_u32 s37, s51, -1
	s_add_i32 s38, 0, 0x10000
	v_add_u32_e32 v154, s38, v144
	ds_read_b128 v[140:143], v154
	ds_read_b128 v[146:149], v154 offset:1024
	ds_read_b128 v[150:153], v154 offset:2048
	ds_read_b128 v[154:157], v154 offset:3072
	s_cmp_eq_u32 s49, 12
	s_cselect_b32 s55, s15, s37
	s_cselect_b32 s54, s16, s36
	s_cselect_b32 s53, s13, s35
	s_cselect_b32 s52, s17, s34
	v_lshl_add_u64 v[166:167], s[50:51], 0, v[136:137]
	s_add_i32 m0, s31, 0xc000
	ds_read_b128 v[158:161], v145
	ds_read_b128 v[162:165], v145 offset:1024
	ds_read_b128 v[180:183], v145 offset:2048
	ds_read_b128 v[184:187], v145 offset:3072
	ds_read_b128 v[188:191], v145 offset:4096
	ds_read_b128 v[192:195], v145 offset:5120
	ds_read_b128 v[196:199], v145 offset:6144
	ds_read_b128 v[200:203], v145 offset:7168
	global_load_lds_dwordx4 v[166:167], off
	s_add_i32 m0, s31, 0xe000
	v_lshl_add_u64 v[166:167], s[50:51], 0, v[138:139]
	global_load_lds_dwordx4 v[166:167], off
	s_waitcnt lgkmcnt(8)
	s_barrier
	s_waitcnt lgkmcnt(0)
	v_mfma_f32_16x16x32_bf16 v[124:127], v[140:143], v[158:161], v[124:127]
	v_mfma_f32_16x16x32_bf16 v[120:123], v[150:153], v[158:161], v[120:123]
	v_mfma_f32_16x16x32_bf16 v[116:119], v[140:143], v[180:183], v[116:119]
	v_mfma_f32_16x16x32_bf16 v[112:115], v[150:153], v[180:183], v[112:115]
	v_mfma_f32_16x16x32_bf16 v[108:111], v[140:143], v[188:191], v[108:111]
	v_mfma_f32_16x16x32_bf16 v[104:107], v[150:153], v[188:191], v[104:107]
	v_mfma_f32_16x16x32_bf16 v[100:103], v[140:143], v[196:199], v[100:103]
	v_mfma_f32_16x16x32_bf16 v[96:99], v[150:153], v[196:199], v[96:99]
	v_mfma_f32_16x16x32_bf16 v[124:127], v[146:149], v[162:165], v[124:127]
	v_mfma_f32_16x16x32_bf16 v[120:123], v[154:157], v[162:165], v[120:123]
	v_mfma_f32_16x16x32_bf16 v[116:119], v[146:149], v[184:187], v[116:119]
	v_mfma_f32_16x16x32_bf16 v[112:115], v[154:157], v[184:187], v[112:115]
	v_mfma_f32_16x16x32_bf16 v[108:111], v[146:149], v[192:195], v[108:111]
	v_mfma_f32_16x16x32_bf16 v[104:107], v[154:157], v[192:195], v[104:107]
	v_mfma_f32_16x16x32_bf16 v[100:103], v[146:149], v[200:203], v[100:103]
	v_mfma_f32_16x16x32_bf16 v[96:99], v[154:157], v[200:203], v[96:99]
	s_barrier
	s_add_i32 s39, 0, 0x14000
	v_add_u32_e32 v166, s39, v144
	s_add_i32 s36, s38, s30
	ds_read_b128 v[204:207], v166
	ds_read_b128 v[208:211], v166 offset:1024
	ds_read_b128 v[212:215], v166 offset:2048
	ds_read_b128 v[216:219], v166 offset:3072
	v_lshl_add_u64 v[166:167], s[52:53], 0, v[130:131]
	s_mov_b32 m0, s36
	v_lshl_add_u64 v[172:173], s[52:53], 0, v[134:135]
	global_load_lds_dwordx4 v[166:167], off
	s_add_i32 m0, s36, 0x2000
	s_nop 0
	global_load_lds_dwordx4 v[172:173], off
	s_barrier
	s_waitcnt lgkmcnt(0)
	v_mfma_f32_16x16x32_bf16 v[68:71], v[204:207], v[158:161], v[68:71]
	v_mfma_f32_16x16x32_bf16 v[64:67], v[212:215], v[158:161], v[64:67]
	v_mfma_f32_16x16x32_bf16 v[52:55], v[204:207], v[180:183], v[52:55]
	v_mfma_f32_16x16x32_bf16 v[48:51], v[212:215], v[180:183], v[48:51]
	v_mfma_f32_16x16x32_bf16 v[44:47], v[204:207], v[188:191], v[44:47]
	v_mfma_f32_16x16x32_bf16 v[40:43], v[212:215], v[188:191], v[40:43]
	v_mfma_f32_16x16x32_bf16 v[36:39], v[204:207], v[196:199], v[36:39]
	v_mfma_f32_16x16x32_bf16 v[32:35], v[212:215], v[196:199], v[32:35]
	v_mfma_f32_16x16x32_bf16 v[68:71], v[208:211], v[162:165], v[68:71]
	v_mfma_f32_16x16x32_bf16 v[64:67], v[216:219], v[162:165], v[64:67]
	v_mfma_f32_16x16x32_bf16 v[52:55], v[208:211], v[184:187], v[52:55]
	v_mfma_f32_16x16x32_bf16 v[48:51], v[216:219], v[184:187], v[48:51]
	v_mfma_f32_16x16x32_bf16 v[44:47], v[208:211], v[192:195], v[44:47]
	v_mfma_f32_16x16x32_bf16 v[40:43], v[216:219], v[192:195], v[40:43]
	v_mfma_f32_16x16x32_bf16 v[36:39], v[208:211], v[200:203], v[36:39]
	v_mfma_f32_16x16x32_bf16 v[32:35], v[216:219], v[200:203], v[32:35]
	s_mov_b32 m0, s31
	v_lshl_add_u64 v[174:175], s[54:55], 0, v[128:129]
	s_barrier
	ds_read_b128 v[158:161], v145 offset:16384
	ds_read_b128 v[162:165], v145 offset:17408
	ds_read_b128 v[180:183], v145 offset:18432
	ds_read_b128 v[184:187], v145 offset:19456
	ds_read_b128 v[188:191], v145 offset:20480
	ds_read_b128 v[192:195], v145 offset:21504
	ds_read_b128 v[196:199], v145 offset:22528
	ds_read_b128 v[200:203], v145 offset:23552
	global_load_lds_dwordx4 v[174:175], off
	v_lshl_add_u64 v[176:177], s[54:55], 0, v[132:133]
	s_mov_b32 m0, s45
	s_nop 0
	global_load_lds_dwordx4 v[176:177], off
	s_barrier
	s_waitcnt lgkmcnt(0)
	v_mfma_f32_16x16x32_bf16 v[92:95], v[140:143], v[158:161], v[92:95]
	v_mfma_f32_16x16x32_bf16 v[88:91], v[150:153], v[158:161], v[88:91]
	v_mfma_f32_16x16x32_bf16 v[84:87], v[140:143], v[180:183], v[84:87]
	v_mfma_f32_16x16x32_bf16 v[80:83], v[150:153], v[180:183], v[80:83]
	v_mfma_f32_16x16x32_bf16 v[76:79], v[140:143], v[188:191], v[76:79]
	v_mfma_f32_16x16x32_bf16 v[72:75], v[150:153], v[188:191], v[72:75]
	v_mfma_f32_16x16x32_bf16 v[60:63], v[140:143], v[196:199], v[60:63]
	v_mfma_f32_16x16x32_bf16 v[56:59], v[150:153], v[196:199], v[56:59]
	v_mfma_f32_16x16x32_bf16 v[92:95], v[146:149], v[162:165], v[92:95]
	v_mfma_f32_16x16x32_bf16 v[88:91], v[154:157], v[162:165], v[88:91]
	v_mfma_f32_16x16x32_bf16 v[84:87], v[146:149], v[184:187], v[84:87]
	v_mfma_f32_16x16x32_bf16 v[80:83], v[154:157], v[184:187], v[80:83]
	v_mfma_f32_16x16x32_bf16 v[76:79], v[146:149], v[192:195], v[76:79]
	v_mfma_f32_16x16x32_bf16 v[72:75], v[154:157], v[192:195], v[72:75]
	v_mfma_f32_16x16x32_bf16 v[60:63], v[146:149], v[200:203], v[60:63]
	v_mfma_f32_16x16x32_bf16 v[56:59], v[154:157], v[200:203], v[56:59]
	s_barrier
	s_add_u32 s36, s52, 0x40000
	s_addc_u32 s37, s53, 0
	s_add_i32 s38, s39, s30
	v_lshl_add_u64 v[140:141], s[36:37], 0, v[130:131]
	s_mov_b32 m0, s38
	s_nop 0
	global_load_lds_dwordx4 v[140:141], off
	s_add_i32 m0, s38, 0x2000
	v_lshl_add_u64 v[140:141], s[36:37], 0, v[134:135]
	global_load_lds_dwordx4 v[140:141], off
	s_waitcnt vmcnt(6)
	s_barrier
	v_mfma_f32_16x16x32_bf16 v[28:31], v[204:207], v[158:161], v[28:31]
	v_mfma_f32_16x16x32_bf16 v[24:27], v[212:215], v[158:161], v[24:27]
	v_mfma_f32_16x16x32_bf16 v[20:23], v[204:207], v[180:183], v[20:23]
	v_mfma_f32_16x16x32_bf16 v[16:19], v[212:215], v[180:183], v[16:19]
	v_mfma_f32_16x16x32_bf16 v[12:15], v[204:207], v[188:191], v[12:15]
	v_mfma_f32_16x16x32_bf16 v[8:11], v[212:215], v[188:191], v[8:11]
	v_mfma_f32_16x16x32_bf16 v[4:7], v[204:207], v[196:199], v[4:7]
	v_mfma_f32_16x16x32_bf16 v[0:3], v[212:215], v[196:199], v[0:3]
	v_mfma_f32_16x16x32_bf16 v[28:31], v[208:211], v[162:165], v[28:31]
	v_mfma_f32_16x16x32_bf16 v[24:27], v[216:219], v[162:165], v[24:27]
	v_mfma_f32_16x16x32_bf16 v[20:23], v[208:211], v[184:187], v[20:23]
	v_mfma_f32_16x16x32_bf16 v[16:19], v[216:219], v[184:187], v[16:19]
	v_mfma_f32_16x16x32_bf16 v[12:15], v[208:211], v[192:195], v[12:15]
	v_mfma_f32_16x16x32_bf16 v[8:11], v[216:219], v[192:195], v[8:11]
	v_mfma_f32_16x16x32_bf16 v[4:7], v[208:211], v[200:203], v[4:7]
	v_mfma_f32_16x16x32_bf16 v[0:3], v[216:219], v[200:203], v[0:3]
	s_add_i32 s38, 0, 0x18000
	v_add_u32_e32 v154, s38, v144
	s_barrier
	ds_read_b128 v[140:143], v154
	ds_read_b128 v[146:149], v154 offset:1024
	ds_read_b128 v[150:153], v154 offset:2048
	ds_read_b128 v[154:157], v154 offset:3072
	s_add_u32 s36, s54, 0x40000
	s_addc_u32 s37, s55, 0
	s_mov_b32 m0, s56
	v_lshl_add_u64 v[178:179], s[36:37], 0, v[128:129]
	ds_read_b128 v[158:161], v145 offset:32768
	ds_read_b128 v[162:165], v145 offset:33792
	ds_read_b128 v[180:183], v145 offset:34816
	ds_read_b128 v[184:187], v145 offset:35840
	ds_read_b128 v[188:191], v145 offset:36864
	ds_read_b128 v[192:195], v145 offset:37888
	ds_read_b128 v[196:199], v145 offset:38912
	ds_read_b128 v[200:203], v145 offset:39936
	global_load_lds_dwordx4 v[178:179], off
	v_lshl_add_u64 v[178:179], s[36:37], 0, v[132:133]
	s_mov_b32 m0, s57
	s_nop 0
	global_load_lds_dwordx4 v[178:179], off
	s_waitcnt lgkmcnt(8)
	s_barrier
	s_waitcnt lgkmcnt(0)
	v_mfma_f32_16x16x32_bf16 v[124:127], v[140:143], v[158:161], v[124:127]
	v_mfma_f32_16x16x32_bf16 v[120:123], v[150:153], v[158:161], v[120:123]
	v_mfma_f32_16x16x32_bf16 v[116:119], v[140:143], v[180:183], v[116:119]
	v_mfma_f32_16x16x32_bf16 v[112:115], v[150:153], v[180:183], v[112:115]
	v_mfma_f32_16x16x32_bf16 v[108:111], v[140:143], v[188:191], v[108:111]
	v_mfma_f32_16x16x32_bf16 v[104:107], v[150:153], v[188:191], v[104:107]
	v_mfma_f32_16x16x32_bf16 v[100:103], v[140:143], v[196:199], v[100:103]
	v_mfma_f32_16x16x32_bf16 v[96:99], v[150:153], v[196:199], v[96:99]
	v_mfma_f32_16x16x32_bf16 v[124:127], v[146:149], v[162:165], v[124:127]
	v_mfma_f32_16x16x32_bf16 v[120:123], v[154:157], v[162:165], v[120:123]
	v_mfma_f32_16x16x32_bf16 v[116:119], v[146:149], v[184:187], v[116:119]
	v_mfma_f32_16x16x32_bf16 v[112:115], v[154:157], v[184:187], v[112:115]
	v_mfma_f32_16x16x32_bf16 v[108:111], v[146:149], v[192:195], v[108:111]
	v_mfma_f32_16x16x32_bf16 v[104:107], v[154:157], v[192:195], v[104:107]
	v_mfma_f32_16x16x32_bf16 v[100:103], v[146:149], v[200:203], v[100:103]
	v_mfma_f32_16x16x32_bf16 v[96:99], v[154:157], v[200:203], v[96:99]
	s_barrier
	s_add_i32 s39, 0, 0x1c000
	s_add_i32 s36, s38, s30
	v_add_u32_e32 v168, s39, v144
	v_lshl_add_u64 v[166:167], v[166:167], 0, s[88:89]
	s_mov_b32 m0, s36
	ds_read_b128 v[204:207], v168
	ds_read_b128 v[208:211], v168 offset:1024
	ds_read_b128 v[212:215], v168 offset:2048
	ds_read_b128 v[216:219], v168 offset:3072
	global_load_lds_dwordx4 v[166:167], off
	s_add_i32 m0, s36, 0x2000
	v_lshl_add_u64 v[166:167], v[172:173], 0, s[88:89]
	global_load_lds_dwordx4 v[166:167], off
	s_barrier
	s_waitcnt lgkmcnt(0)
	v_mfma_f32_16x16x32_bf16 v[68:71], v[204:207], v[158:161], v[68:71]
	v_mfma_f32_16x16x32_bf16 v[64:67], v[212:215], v[158:161], v[64:67]
	v_mfma_f32_16x16x32_bf16 v[52:55], v[204:207], v[180:183], v[52:55]
	v_mfma_f32_16x16x32_bf16 v[48:51], v[212:215], v[180:183], v[48:51]
	v_mfma_f32_16x16x32_bf16 v[44:47], v[204:207], v[188:191], v[44:47]
	v_mfma_f32_16x16x32_bf16 v[40:43], v[212:215], v[188:191], v[40:43]
	v_mfma_f32_16x16x32_bf16 v[36:39], v[204:207], v[196:199], v[36:39]
	v_mfma_f32_16x16x32_bf16 v[32:35], v[212:215], v[196:199], v[32:35]
	v_mfma_f32_16x16x32_bf16 v[68:71], v[208:211], v[162:165], v[68:71]
	v_mfma_f32_16x16x32_bf16 v[64:67], v[216:219], v[162:165], v[64:67]
	v_mfma_f32_16x16x32_bf16 v[52:55], v[208:211], v[184:187], v[52:55]
	v_mfma_f32_16x16x32_bf16 v[48:51], v[216:219], v[184:187], v[48:51]
	v_mfma_f32_16x16x32_bf16 v[44:47], v[208:211], v[192:195], v[44:47]
	v_mfma_f32_16x16x32_bf16 v[40:43], v[216:219], v[192:195], v[40:43]
	v_mfma_f32_16x16x32_bf16 v[36:39], v[208:211], v[200:203], v[36:39]
	v_mfma_f32_16x16x32_bf16 v[32:35], v[216:219], v[200:203], v[32:35]
	s_mov_b32 m0, s60
	v_lshl_add_u64 v[166:167], v[174:175], 0, s[88:89]
	s_barrier
	ds_read_b128 v[158:161], v145 offset:49152
	ds_read_b128 v[162:165], v145 offset:50176
	ds_read_b128 v[180:183], v145 offset:51200
	ds_read_b128 v[184:187], v145 offset:52224
	ds_read_b128 v[188:191], v145 offset:53248
	ds_read_b128 v[192:195], v145 offset:54272
	ds_read_b128 v[196:199], v145 offset:55296
	ds_read_b128 v[200:203], v145 offset:56320
	global_load_lds_dwordx4 v[166:167], off
	v_lshl_add_u64 v[166:167], v[176:177], 0, s[88:89]
	s_mov_b32 m0, s61
	s_nop 0
	global_load_lds_dwordx4 v[166:167], off
	s_barrier
	s_waitcnt lgkmcnt(0)
	v_mfma_f32_16x16x32_bf16 v[92:95], v[140:143], v[158:161], v[92:95]
	v_mfma_f32_16x16x32_bf16 v[88:91], v[150:153], v[158:161], v[88:91]
	v_mfma_f32_16x16x32_bf16 v[84:87], v[140:143], v[180:183], v[84:87]
	v_mfma_f32_16x16x32_bf16 v[80:83], v[150:153], v[180:183], v[80:83]
	v_mfma_f32_16x16x32_bf16 v[76:79], v[140:143], v[188:191], v[76:79]
	v_mfma_f32_16x16x32_bf16 v[72:75], v[150:153], v[188:191], v[72:75]
	v_mfma_f32_16x16x32_bf16 v[60:63], v[140:143], v[196:199], v[60:63]
	v_mfma_f32_16x16x32_bf16 v[56:59], v[150:153], v[196:199], v[56:59]
	v_mfma_f32_16x16x32_bf16 v[92:95], v[146:149], v[162:165], v[92:95]
	v_mfma_f32_16x16x32_bf16 v[88:91], v[154:157], v[162:165], v[88:91]
	v_mfma_f32_16x16x32_bf16 v[84:87], v[146:149], v[184:187], v[84:87]
	v_mfma_f32_16x16x32_bf16 v[80:83], v[154:157], v[184:187], v[80:83]
	v_mfma_f32_16x16x32_bf16 v[76:79], v[146:149], v[192:195], v[76:79]
	v_mfma_f32_16x16x32_bf16 v[72:75], v[154:157], v[192:195], v[72:75]
	v_mfma_f32_16x16x32_bf16 v[60:63], v[146:149], v[200:203], v[60:63]
	v_mfma_f32_16x16x32_bf16 v[56:59], v[154:157], v[200:203], v[56:59]
	s_barrier
	s_add_u32 s36, s52, 0x40080
	s_addc_u32 s37, s53, 0
	s_add_i32 s38, s39, s30
	v_lshl_add_u64 v[140:141], s[36:37], 0, v[130:131]
	s_mov_b32 m0, s38
	s_nop 0
	global_load_lds_dwordx4 v[140:141], off
	s_add_i32 m0, s38, 0x2000
	v_lshl_add_u64 v[140:141], s[36:37], 0, v[134:135]
	global_load_lds_dwordx4 v[140:141], off
	s_waitcnt vmcnt(6)
	s_barrier
	v_mfma_f32_16x16x32_bf16 v[28:31], v[204:207], v[158:161], v[28:31]
	v_mfma_f32_16x16x32_bf16 v[24:27], v[212:215], v[158:161], v[24:27]
	v_mfma_f32_16x16x32_bf16 v[20:23], v[204:207], v[180:183], v[20:23]
	v_mfma_f32_16x16x32_bf16 v[16:19], v[212:215], v[180:183], v[16:19]
	v_mfma_f32_16x16x32_bf16 v[12:15], v[204:207], v[188:191], v[12:15]
	v_mfma_f32_16x16x32_bf16 v[8:11], v[212:215], v[188:191], v[8:11]
	v_mfma_f32_16x16x32_bf16 v[4:7], v[204:207], v[196:199], v[4:7]
	v_mfma_f32_16x16x32_bf16 v[0:3], v[212:215], v[196:199], v[0:3]
	v_mfma_f32_16x16x32_bf16 v[28:31], v[208:211], v[162:165], v[28:31]
	v_mfma_f32_16x16x32_bf16 v[24:27], v[216:219], v[162:165], v[24:27]
	v_mfma_f32_16x16x32_bf16 v[20:23], v[208:211], v[184:187], v[20:23]
	v_mfma_f32_16x16x32_bf16 v[16:19], v[216:219], v[184:187], v[16:19]
	v_mfma_f32_16x16x32_bf16 v[12:15], v[208:211], v[192:195], v[12:15]
	v_mfma_f32_16x16x32_bf16 v[8:11], v[216:219], v[192:195], v[8:11]
	v_mfma_f32_16x16x32_bf16 v[4:7], v[208:211], v[200:203], v[4:7]
	v_mfma_f32_16x16x32_bf16 v[0:3], v[216:219], v[200:203], v[0:3]
	s_add_i32 s49, s49, 2
	s_add_u32 s50, s50, 0x100
	s_addc_u32 s51, s51, 0
	s_add_u32 s34, s34, 0x100
	s_addc_u32 s35, s35, 0
	s_cmp_gt_u32 s49, 13
	s_barrier
	s_cbranch_scc0 .LBB0_264
	v_mov_b32_e32 v141, v171
	s_lshl_b32 s13, s48, 8
	s_or_b32 s13, s13, s59
	v_lshrrev_b32_e32 v140, 1, v141
	s_cmpk_lg_i32 s13, 0x400
	v_and_or_b32 v140, v140, 24, s13
	s_mov_b64 s[48:49], -1
	s_cbranch_scc0 .LBB0_267
	v_add_u32_e32 v142, 0xfffff4d8, v140
	v_add_u32_e32 v143, 0xfffff518, v140
	v_cmp_gt_u32_e32 vcc, 16, v142
	s_movk_i32 s13, 0x720
	s_mov_b64 s[48:49], 0
	v_cndmask_b32_e32 v142, -1, v143, vcc
	v_cmp_ne_u32_e32 vcc, s13, v140
	s_nop 1
	v_cndmask_b32_e32 v168, 32, v142, vcc

.LBB0_709:
	s_add_i32 s70, s49, 2
	s_add_u32 s36, s50, 0x80
	s_addc_u32 s37, s51, 0
	s_add_i32 s38, 0, 0x10000
	v_add_u32_e32 v146, s38, v152
	ds_read_b128 v[134:137], v146
	ds_read_b128 v[138:141], v146 offset:1024
	ds_read_b128 v[142:145], v146 offset:2048
	ds_read_b128 v[146:149], v146 offset:3072
	s_cmp_eq_u32 s66, s49
	s_cselect_b32 s53, s43, s37
	s_cselect_b32 s52, s42, s36
	s_cselect_b32 s55, s45, s35
	s_cselect_b32 s54, s44, s34
	v_lshl_add_u64 v[150:151], s[50:51], 0, v[130:131]
	s_add_i32 m0, s29, 0xc000
	ds_read_b128 v[154:157], v153
	ds_read_b128 v[158:161], v153 offset:1024
	ds_read_b128 v[162:165], v153 offset:2048
	ds_read_b128 v[172:175], v153 offset:3072
	ds_read_b128 v[176:179], v153 offset:4096
	ds_read_b128 v[180:183], v153 offset:5120
	ds_read_b128 v[184:187], v153 offset:6144
	ds_read_b128 v[188:191], v153 offset:7168
	global_load_lds_dwordx4 v[150:151], off
	s_add_i32 m0, s29, 0xe000
	v_lshl_add_u64 v[150:151], s[50:51], 0, v[132:133]
	global_load_lds_dwordx4 v[150:151], off
	s_waitcnt lgkmcnt(8)
	s_barrier
	s_waitcnt lgkmcnt(0)
	v_mfma_f32_16x16x32_bf16 v[124:127], v[134:137], v[154:157], v[124:127]
	v_mfma_f32_16x16x32_bf16 v[104:107], v[142:145], v[154:157], v[104:107]
	v_mfma_f32_16x16x32_bf16 v[120:123], v[134:137], v[162:165], v[120:123]
	v_mfma_f32_16x16x32_bf16 v[92:95], v[142:145], v[162:165], v[92:95]
	v_mfma_f32_16x16x32_bf16 v[116:119], v[134:137], v[176:179], v[116:119]
	v_mfma_f32_16x16x32_bf16 v[84:87], v[142:145], v[176:179], v[84:87]
	v_mfma_f32_16x16x32_bf16 v[112:115], v[134:137], v[184:187], v[112:115]
	v_mfma_f32_16x16x32_bf16 v[80:83], v[142:145], v[184:187], v[80:83]
	v_mfma_f32_16x16x32_bf16 v[124:127], v[138:141], v[158:161], v[124:127]
	v_mfma_f32_16x16x32_bf16 v[104:107], v[146:149], v[158:161], v[104:107]
	v_mfma_f32_16x16x32_bf16 v[120:123], v[138:141], v[172:175], v[120:123]
	v_mfma_f32_16x16x32_bf16 v[92:95], v[146:149], v[172:175], v[92:95]
	v_mfma_f32_16x16x32_bf16 v[116:119], v[138:141], v[180:183], v[116:119]
	v_mfma_f32_16x16x32_bf16 v[84:87], v[146:149], v[180:183], v[84:87]
	v_mfma_f32_16x16x32_bf16 v[112:115], v[138:141], v[188:191], v[112:115]
	v_mfma_f32_16x16x32_bf16 v[80:83], v[146:149], v[188:191], v[80:83]
	s_barrier
	s_add_i32 s39, 0, 0x14000
	v_add_u32_e32 v150, s39, v152
	s_add_i32 s36, s38, s28
	ds_read_b128 v[192:195], v150
	ds_read_b128 v[196:199], v150 offset:1024
	ds_read_b128 v[200:203], v150 offset:2048
	ds_read_b128 v[204:207], v150 offset:3072
	v_lshl_add_u64 v[150:151], s[54:55], 0, v[168:169]
	s_mov_b32 m0, s36
	v_lshl_add_u64 v[166:167], s[54:55], 0, v[128:129]
	global_load_lds_dwordx4 v[150:151], off
	s_add_i32 m0, s36, 0x2000
	s_nop 0
	global_load_lds_dwordx4 v[166:167], off
	s_barrier
	s_waitcnt lgkmcnt(0)
	v_mfma_f32_16x16x32_bf16 v[60:63], v[192:195], v[154:157], v[60:63]
	v_mfma_f32_16x16x32_bf16 v[48:51], v[200:203], v[154:157], v[48:51]
	v_mfma_f32_16x16x32_bf16 v[56:59], v[192:195], v[162:165], v[56:59]
	v_mfma_f32_16x16x32_bf16 v[40:43], v[200:203], v[162:165], v[40:43]
	v_mfma_f32_16x16x32_bf16 v[52:55], v[192:195], v[176:179], v[52:55]
	v_mfma_f32_16x16x32_bf16 v[36:39], v[200:203], v[176:179], v[36:39]
	v_mfma_f32_16x16x32_bf16 v[44:47], v[192:195], v[184:187], v[44:47]
	v_mfma_f32_16x16x32_bf16 v[28:31], v[200:203], v[184:187], v[28:31]
	v_mfma_f32_16x16x32_bf16 v[60:63], v[196:199], v[158:161], v[60:63]
	v_mfma_f32_16x16x32_bf16 v[48:51], v[204:207], v[158:161], v[48:51]
	v_mfma_f32_16x16x32_bf16 v[56:59], v[196:199], v[172:175], v[56:59]
	v_mfma_f32_16x16x32_bf16 v[40:43], v[204:207], v[172:175], v[40:43]
	v_mfma_f32_16x16x32_bf16 v[52:55], v[196:199], v[180:183], v[52:55]
	v_mfma_f32_16x16x32_bf16 v[36:39], v[204:207], v[180:183], v[36:39]
	v_mfma_f32_16x16x32_bf16 v[44:47], v[196:199], v[188:191], v[44:47]
	v_mfma_f32_16x16x32_bf16 v[28:31], v[204:207], v[188:191], v[28:31]
	s_mov_b32 m0, s29
	v_lshl_add_u64 v[208:209], s[52:53], 0, v[168:169]
	s_barrier
	ds_read_b128 v[154:157], v153 offset:16384
	ds_read_b128 v[158:161], v153 offset:17408
	ds_read_b128 v[162:165], v153 offset:18432
	ds_read_b128 v[172:175], v153 offset:19456
	ds_read_b128 v[176:179], v153 offset:20480
	ds_read_b128 v[180:183], v153 offset:21504
	ds_read_b128 v[184:187], v153 offset:22528
	ds_read_b128 v[188:191], v153 offset:23552
	global_load_lds_dwordx4 v[208:209], off
	v_lshl_add_u64 v[210:211], s[52:53], 0, v[128:129]
	s_mov_b32 m0, s30
	s_nop 0
	global_load_lds_dwordx4 v[210:211], off
	s_barrier
	s_waitcnt lgkmcnt(0)
	v_mfma_f32_16x16x32_bf16 v[108:111], v[134:137], v[154:157], v[108:111]
	v_mfma_f32_16x16x32_bf16 v[76:79], v[142:145], v[154:157], v[76:79]
	v_mfma_f32_16x16x32_bf16 v[100:103], v[134:137], v[162:165], v[100:103]
	v_mfma_f32_16x16x32_bf16 v[72:75], v[142:145], v[162:165], v[72:75]
	v_mfma_f32_16x16x32_bf16 v[96:99], v[134:137], v[176:179], v[96:99]
	v_mfma_f32_16x16x32_bf16 v[68:71], v[142:145], v[176:179], v[68:71]
	v_mfma_f32_16x16x32_bf16 v[88:91], v[134:137], v[184:187], v[88:91]
	v_mfma_f32_16x16x32_bf16 v[64:67], v[142:145], v[184:187], v[64:67]
	v_mfma_f32_16x16x32_bf16 v[108:111], v[138:141], v[158:161], v[108:111]
	v_mfma_f32_16x16x32_bf16 v[76:79], v[146:149], v[158:161], v[76:79]
	v_mfma_f32_16x16x32_bf16 v[100:103], v[138:141], v[172:175], v[100:103]
	v_mfma_f32_16x16x32_bf16 v[72:75], v[146:149], v[172:175], v[72:75]
	v_mfma_f32_16x16x32_bf16 v[96:99], v[138:141], v[180:183], v[96:99]
	v_mfma_f32_16x16x32_bf16 v[68:71], v[146:149], v[180:183], v[68:71]
	v_mfma_f32_16x16x32_bf16 v[88:91], v[138:141], v[188:191], v[88:91]
	v_mfma_f32_16x16x32_bf16 v[64:67], v[146:149], v[188:191], v[64:67]
	s_barrier
	s_add_u32 s36, s54, s10
	s_addc_u32 s37, s55, 0
	s_add_i32 s38, s39, s28
	v_lshl_add_u64 v[212:213], s[36:37], 0, v[168:169]
	s_mov_b32 m0, s38
	v_lshl_add_u64 v[214:215], s[36:37], 0, v[128:129]
	global_load_lds_dwordx4 v[212:213], off
	s_add_i32 m0, s38, 0x2000
	s_nop 0
	global_load_lds_dwordx4 v[214:215], off
	s_waitcnt vmcnt(6)
	s_barrier
	v_mfma_f32_16x16x32_bf16 v[32:35], v[192:195], v[154:157], v[32:35]
	v_mfma_f32_16x16x32_bf16 v[12:15], v[200:203], v[154:157], v[12:15]
	v_mfma_f32_16x16x32_bf16 v[24:27], v[192:195], v[162:165], v[24:27]
	v_mfma_f32_16x16x32_bf16 v[8:11], v[200:203], v[162:165], v[8:11]
	v_mfma_f32_16x16x32_bf16 v[20:23], v[192:195], v[176:179], v[20:23]
	v_mfma_f32_16x16x32_bf16 v[4:7], v[200:203], v[176:179], v[4:7]
	v_mfma_f32_16x16x32_bf16 v[16:19], v[192:195], v[184:187], v[16:19]
	v_mfma_f32_16x16x32_bf16 v[0:3], v[200:203], v[184:187], v[0:3]
	v_mfma_f32_16x16x32_bf16 v[32:35], v[196:199], v[158:161], v[32:35]
	v_mfma_f32_16x16x32_bf16 v[12:15], v[204:207], v[158:161], v[12:15]
	v_mfma_f32_16x16x32_bf16 v[24:27], v[196:199], v[172:175], v[24:27]
	v_mfma_f32_16x16x32_bf16 v[8:11], v[204:207], v[172:175], v[8:11]
	v_mfma_f32_16x16x32_bf16 v[20:23], v[196:199], v[180:183], v[20:23]
	v_mfma_f32_16x16x32_bf16 v[4:7], v[204:207], v[180:183], v[4:7]
	v_mfma_f32_16x16x32_bf16 v[16:19], v[196:199], v[188:191], v[16:19]
	v_mfma_f32_16x16x32_bf16 v[0:3], v[204:207], v[188:191], v[0:3]
	s_add_i32 s38, 0, 0x18000
	v_add_u32_e32 v146, s38, v152
	s_barrier
	ds_read_b128 v[134:137], v146
	ds_read_b128 v[138:141], v146 offset:1024
	ds_read_b128 v[142:145], v146 offset:2048
	ds_read_b128 v[146:149], v146 offset:3072
	s_add_u32 s36, s52, s10
	s_addc_u32 s37, s53, 0
	s_mov_b32 m0, s31
	v_lshl_add_u64 v[192:193], s[36:37], 0, v[168:169]
	ds_read_b128 v[154:157], v153 offset:32768
	ds_read_b128 v[158:161], v153 offset:33792
	ds_read_b128 v[162:165], v153 offset:34816
	ds_read_b128 v[172:175], v153 offset:35840
	ds_read_b128 v[176:179], v153 offset:36864
	ds_read_b128 v[180:183], v153 offset:37888
	ds_read_b128 v[184:187], v153 offset:38912
	ds_read_b128 v[188:191], v153 offset:39936
	global_load_lds_dwordx4 v[192:193], off
	v_lshl_add_u64 v[192:193], s[36:37], 0, v[128:129]
	s_mov_b32 m0, s56
	s_nop 0
	global_load_lds_dwordx4 v[192:193], off
	s_waitcnt lgkmcnt(8)
	s_barrier
	s_waitcnt lgkmcnt(0)
	v_mfma_f32_16x16x32_bf16 v[124:127], v[134:137], v[154:157], v[124:127]
	v_mfma_f32_16x16x32_bf16 v[104:107], v[142:145], v[154:157], v[104:107]
	v_mfma_f32_16x16x32_bf16 v[120:123], v[134:137], v[162:165], v[120:123]
	v_mfma_f32_16x16x32_bf16 v[92:95], v[142:145], v[162:165], v[92:95]
	v_mfma_f32_16x16x32_bf16 v[116:119], v[134:137], v[176:179], v[116:119]
	v_mfma_f32_16x16x32_bf16 v[84:87], v[142:145], v[176:179], v[84:87]
	v_mfma_f32_16x16x32_bf16 v[112:115], v[134:137], v[184:187], v[112:115]
	v_mfma_f32_16x16x32_bf16 v[80:83], v[142:145], v[184:187], v[80:83]
	v_mfma_f32_16x16x32_bf16 v[124:127], v[138:141], v[158:161], v[124:127]
	v_mfma_f32_16x16x32_bf16 v[104:107], v[146:149], v[158:161], v[104:107]
	v_mfma_f32_16x16x32_bf16 v[120:123], v[138:141], v[172:175], v[120:123]
	v_mfma_f32_16x16x32_bf16 v[92:95], v[146:149], v[172:175], v[92:95]
	v_mfma_f32_16x16x32_bf16 v[116:119], v[138:141], v[180:183], v[116:119]
	v_mfma_f32_16x16x32_bf16 v[84:87], v[146:149], v[180:183], v[84:87]
	v_mfma_f32_16x16x32_bf16 v[112:115], v[138:141], v[188:191], v[112:115]
	v_mfma_f32_16x16x32_bf16 v[80:83], v[146:149], v[188:191], v[80:83]
	s_barrier
	s_add_i32 s36, 0, 0x1c000
	s_add_i32 s37, s38, s28
	v_add_u32_e32 v204, s36, v152
	v_lshl_add_u64 v[150:151], v[150:151], 0, s[88:89]
	s_mov_b32 m0, s37
	ds_read_b128 v[192:195], v204
	ds_read_b128 v[196:199], v204 offset:1024
	ds_read_b128 v[200:203], v204 offset:2048
	ds_read_b128 v[204:207], v204 offset:3072
	global_load_lds_dwordx4 v[150:151], off
	s_add_i32 m0, s37, 0x2000
	v_lshl_add_u64 v[150:151], v[166:167], 0, s[88:89]
	global_load_lds_dwordx4 v[150:151], off
	s_barrier
	s_waitcnt lgkmcnt(0)
	v_mfma_f32_16x16x32_bf16 v[60:63], v[192:195], v[154:157], v[60:63]
	v_mfma_f32_16x16x32_bf16 v[48:51], v[200:203], v[154:157], v[48:51]
	v_mfma_f32_16x16x32_bf16 v[56:59], v[192:195], v[162:165], v[56:59]
	v_mfma_f32_16x16x32_bf16 v[40:43], v[200:203], v[162:165], v[40:43]
	v_mfma_f32_16x16x32_bf16 v[52:55], v[192:195], v[176:179], v[52:55]
	v_mfma_f32_16x16x32_bf16 v[36:39], v[200:203], v[176:179], v[36:39]
	v_mfma_f32_16x16x32_bf16 v[44:47], v[192:195], v[184:187], v[44:47]
	v_mfma_f32_16x16x32_bf16 v[28:31], v[200:203], v[184:187], v[28:31]
	v_mfma_f32_16x16x32_bf16 v[60:63], v[196:199], v[158:161], v[60:63]
	v_mfma_f32_16x16x32_bf16 v[48:51], v[204:207], v[158:161], v[48:51]
	v_mfma_f32_16x16x32_bf16 v[56:59], v[196:199], v[172:175], v[56:59]
	v_mfma_f32_16x16x32_bf16 v[40:43], v[204:207], v[172:175], v[40:43]
	v_mfma_f32_16x16x32_bf16 v[52:55], v[196:199], v[180:183], v[52:55]
	v_mfma_f32_16x16x32_bf16 v[36:39], v[204:207], v[180:183], v[36:39]
	v_mfma_f32_16x16x32_bf16 v[44:47], v[196:199], v[188:191], v[44:47]
	v_mfma_f32_16x16x32_bf16 v[28:31], v[204:207], v[188:191], v[28:31]
	s_mov_b32 m0, s61
	v_lshl_add_u64 v[150:151], v[208:209], 0, s[88:89]
	s_barrier
	ds_read_b128 v[154:157], v153 offset:49152
	ds_read_b128 v[158:161], v153 offset:50176
	ds_read_b128 v[162:165], v153 offset:51200
	ds_read_b128 v[172:175], v153 offset:52224
	ds_read_b128 v[176:179], v153 offset:53248
	ds_read_b128 v[180:183], v153 offset:54272
	ds_read_b128 v[184:187], v153 offset:55296
	ds_read_b128 v[188:191], v153 offset:56320
	global_load_lds_dwordx4 v[150:151], off
	v_lshl_add_u64 v[150:151], v[210:211], 0, s[88:89]
	s_mov_b32 m0, s62
	s_nop 0
	global_load_lds_dwordx4 v[150:151], off
	s_barrier
	s_waitcnt lgkmcnt(0)
	v_mfma_f32_16x16x32_bf16 v[108:111], v[134:137], v[154:157], v[108:111]
	v_mfma_f32_16x16x32_bf16 v[76:79], v[142:145], v[154:157], v[76:79]
	v_mfma_f32_16x16x32_bf16 v[100:103], v[134:137], v[162:165], v[100:103]
	v_mfma_f32_16x16x32_bf16 v[72:75], v[142:145], v[162:165], v[72:75]
	v_mfma_f32_16x16x32_bf16 v[96:99], v[134:137], v[176:179], v[96:99]
	v_mfma_f32_16x16x32_bf16 v[68:71], v[142:145], v[176:179], v[68:71]
	v_mfma_f32_16x16x32_bf16 v[88:91], v[134:137], v[184:187], v[88:91]
	v_mfma_f32_16x16x32_bf16 v[64:67], v[142:145], v[184:187], v[64:67]
	v_mfma_f32_16x16x32_bf16 v[108:111], v[138:141], v[158:161], v[108:111]
	v_mfma_f32_16x16x32_bf16 v[76:79], v[146:149], v[158:161], v[76:79]
	v_mfma_f32_16x16x32_bf16 v[100:103], v[138:141], v[172:175], v[100:103]
	v_mfma_f32_16x16x32_bf16 v[72:75], v[146:149], v[172:175], v[72:75]
	v_mfma_f32_16x16x32_bf16 v[96:99], v[138:141], v[180:183], v[96:99]
	v_mfma_f32_16x16x32_bf16 v[68:71], v[146:149], v[180:183], v[68:71]
	v_mfma_f32_16x16x32_bf16 v[88:91], v[138:141], v[188:191], v[88:91]
	v_mfma_f32_16x16x32_bf16 v[64:67], v[146:149], v[188:191], v[64:67]
	s_barrier
	s_add_i32 s36, s36, s28
	v_lshl_add_u64 v[134:135], v[212:213], 0, s[88:89]
	s_mov_b32 m0, s36
	s_nop 0
	global_load_lds_dwordx4 v[134:135], off
	s_add_i32 m0, s36, 0x2000
	v_lshl_add_u64 v[134:135], v[214:215], 0, s[88:89]
	global_load_lds_dwordx4 v[134:135], off
	s_waitcnt vmcnt(6)
	s_barrier
	v_mfma_f32_16x16x32_bf16 v[32:35], v[192:195], v[154:157], v[32:35]
	v_mfma_f32_16x16x32_bf16 v[12:15], v[200:203], v[154:157], v[12:15]
	v_mfma_f32_16x16x32_bf16 v[24:27], v[192:195], v[162:165], v[24:27]
	v_mfma_f32_16x16x32_bf16 v[8:11], v[200:203], v[162:165], v[8:11]
	v_mfma_f32_16x16x32_bf16 v[20:23], v[192:195], v[176:179], v[20:23]
	v_mfma_f32_16x16x32_bf16 v[4:7], v[200:203], v[176:179], v[4:7]
	v_mfma_f32_16x16x32_bf16 v[16:19], v[192:195], v[184:187], v[16:19]
	v_mfma_f32_16x16x32_bf16 v[0:3], v[200:203], v[184:187], v[0:3]
	v_mfma_f32_16x16x32_bf16 v[32:35], v[196:199], v[158:161], v[32:35]
	v_mfma_f32_16x16x32_bf16 v[12:15], v[204:207], v[158:161], v[12:15]
	v_mfma_f32_16x16x32_bf16 v[24:27], v[196:199], v[172:175], v[24:27]
	v_mfma_f32_16x16x32_bf16 v[8:11], v[204:207], v[172:175], v[8:11]
	v_mfma_f32_16x16x32_bf16 v[20:23], v[196:199], v[180:183], v[20:23]
	v_mfma_f32_16x16x32_bf16 v[4:7], v[204:207], v[180:183], v[4:7]
	v_mfma_f32_16x16x32_bf16 v[16:19], v[196:199], v[188:191], v[16:19]
	v_mfma_f32_16x16x32_bf16 v[0:3], v[204:207], v[188:191], v[0:3]
	s_add_u32 s50, s50, 0x100
	s_addc_u32 s51, s51, 0
	s_add_u32 s34, s34, 0x100
	s_addc_u32 s35, s35, 0
	s_cmp_ge_u32 s70, s63
	s_mov_b32 s49, s70
	s_barrier
	s_cbranch_scc0 .LBB0_709
	v_mov_b32_e32 v134, v171
	s_cmpk_gt_i32 s48, 0x7f
	s_mov_b64 s[52:53], -1
	s_cbranch_scc0 .LBB0_712
	s_add_i32 s84, s48, 0xffffff80
	s_lshl_b64 s[34:35], s[84:85], 20
	s_add_u32 s50, s57, s34
	s_addc_u32 s51, s58, s35
	s_mov_b64 s[52:53], 0
